# baseline (speedup 1.0000x reference)
; #define WAIT_V(n) asm volatile("s_waitcnt vmcnt(%0)" ::"n"(n) : "memory")
; template <class Epi>
; DEV void gemm_phase(const u16* __restrict__ A, int lda, const u16* __restrict__ Bt, int K, int nM, int nN, char* shm, const Epi& epi) {
;     ...
;   int t = blockIdx.x;
;   if (t >= nwg) return;
;   int brow, bcol;
;   tile_coords(t, nwg, nM, nN, brow, bcol);
;   const u16* Ab = A + (long)brow * lda;
;   const u16* Bb = Bt + (long)bcol * K;
;   int cur = 0;
;   __syncthreads();
;   GLDS_STAGE(0, Ab, Bb, 0); WAIT_V(0); __syncthreads();
;   for (;;) {
;     const int tn = t + gridDim.x;
;     const bool has_next = tn < nwg;
;     int nbrow = 0, nbcol = 0;
;     if (has_next) tile_coords(tn, nwg, nM, nN, nbrow, nbcol);
;     const u16* nAb = A + (long)nbrow * lda;
;     const u16* nBb = Bt + (long)nbcol * K;
;     f32x4 acc[8][4];
; #pragma unroll
;     for (int m = 0; m < 8; ++m)
; #pragma unroll
;       for (int n = 0; n < 4; ++n) acc[m][n] = f32x4{0.f, 0.f, 0.f, 0.f};
.LBB0_186:
	s_ashr_i32 s17, s16, 31
	s_ashr_i32 s19, s18, 31
	s_lshl_b64 s[20:21], s[16:17], 12
	s_lshl_b64 s[24:25], s[18:19], 12
	s_add_u32 s0, s94, s20
	s_addc_u32 s1, s95, s21
	s_add_u32 s34, s68, s24
	s_addc_u32 s35, s69, s25
	s_add_u32 s28, s68, s28
	s_addc_u32 s29, s69, s29
	s_add_u32 s30, s94, s30
	v_mov_b32_e32 v32, 0
	s_addc_u32 s31, s95, s31
	v_lshl_add_u64 v[138:139], s[0:1], 0, v[128:129]
	v_lshl_add_u64 v[140:141], s[34:35], 0, v[128:129]
	v_lshl_add_u64 v[142:143], s[0:1], 0, v[130:131]
	v_lshl_add_u64 v[144:145], s[34:35], 0, v[130:131]
	v_lshl_add_u64 v[146:147], s[0:1], 0, v[132:133]
	v_lshl_add_u64 v[148:149], s[34:35], 0, v[132:133]
	v_lshl_add_u64 v[150:151], s[0:1], 0, v[134:135]
	v_lshl_add_u64 v[152:153], s[34:35], 0, v[134:135]
	s_mov_b32 s0, 0
	v_mov_b32_e32 v33, v32
	v_mov_b32_e32 v34, v32
	v_mov_b32_e32 v35, v32
	v_mov_b32_e32 v36, v32
	v_mov_b32_e32 v37, v32
	v_mov_b32_e32 v38, v32
	v_mov_b32_e32 v39, v32
	v_mov_b32_e32 v40, v32
	v_mov_b32_e32 v41, v32
	v_mov_b32_e32 v42, v32
	v_mov_b32_e32 v43, v32
	v_mov_b32_e32 v44, v32
	v_mov_b32_e32 v45, v32
	v_mov_b32_e32 v46, v32
	v_mov_b32_e32 v47, v32
	v_mov_b32_e32 v48, v32
	v_mov_b32_e32 v49, v32
	v_mov_b32_e32 v50, v32
	v_mov_b32_e32 v51, v32
	v_mov_b32_e32 v52, v32
	v_mov_b32_e32 v53, v32
	v_mov_b32_e32 v54, v32
	v_mov_b32_e32 v55, v32
	v_mov_b32_e32 v56, v32
	v_mov_b32_e32 v57, v32
	v_mov_b32_e32 v58, v32
	v_mov_b32_e32 v59, v32
	v_mov_b32_e32 v60, v32
	v_mov_b32_e32 v61, v32
	v_mov_b32_e32 v62, v32
	v_mov_b32_e32 v63, v32
	v_mov_b32_e32 v64, v32
	v_mov_b32_e32 v65, v32
	v_mov_b32_e32 v66, v32
	v_mov_b32_e32 v67, v32
	v_mov_b32_e32 v68, v32
	v_mov_b32_e32 v69, v32
	v_mov_b32_e32 v70, v32
	v_mov_b32_e32 v71, v32
	v_mov_b32_e32 v72, v32
	v_mov_b32_e32 v73, v32
	v_mov_b32_e32 v74, v32
	v_mov_b32_e32 v75, v32
	v_mov_b32_e32 v76, v32
	v_mov_b32_e32 v77, v32
	v_mov_b32_e32 v78, v32
	v_mov_b32_e32 v79, v32
	v_mov_b32_e32 v80, v32
	v_mov_b32_e32 v81, v32
	v_mov_b32_e32 v82, v32
	v_mov_b32_e32 v83, v32
	v_mov_b32_e32 v84, v32
	v_mov_b32_e32 v85, v32
	v_mov_b32_e32 v86, v32
	v_mov_b32_e32 v87, v32
	v_mov_b32_e32 v88, v32
	v_mov_b32_e32 v89, v32
	v_mov_b32_e32 v90, v32
	v_mov_b32_e32 v91, v32
	v_mov_b32_e32 v92, v32
	v_mov_b32_e32 v93, v32
	v_mov_b32_e32 v94, v32
	v_mov_b32_e32 v95, v32
	v_mov_b32_e32 v96, v32
	v_mov_b32_e32 v97, v32
	v_mov_b32_e32 v98, v32
	v_mov_b32_e32 v99, v32
	v_mov_b32_e32 v100, v32
	v_mov_b32_e32 v101, v32
	v_mov_b32_e32 v102, v32
	v_mov_b32_e32 v103, v32
	v_mov_b32_e32 v104, v32
	v_mov_b32_e32 v105, v32
	v_mov_b32_e32 v106, v32
	v_mov_b32_e32 v107, v32
	v_mov_b32_e32 v108, v32
	v_mov_b32_e32 v109, v32
	v_mov_b32_e32 v110, v32
	v_mov_b32_e32 v111, v32
	v_mov_b32_e32 v112, v32
	v_mov_b32_e32 v113, v32
	v_mov_b32_e32 v114, v32
	v_mov_b32_e32 v115, v32
	v_mov_b32_e32 v116, v32
	v_mov_b32_e32 v117, v32
	v_mov_b32_e32 v118, v32
	v_mov_b32_e32 v119, v32
	v_mov_b32_e32 v120, v32
	v_mov_b32_e32 v121, v32
	v_mov_b32_e32 v122, v32
	v_mov_b32_e32 v123, v32
	v_mov_b32_e32 v124, v32
	v_mov_b32_e32 v125, v32
	v_mov_b32_e32 v126, v32
	v_mov_b32_e32 v127, v32
	v_mov_b32_e32 v28, v32
	v_mov_b32_e32 v29, v32
	v_mov_b32_e32 v30, v32
	v_mov_b32_e32 v31, v32
	v_mov_b32_e32 v24, v32
	v_mov_b32_e32 v25, v32
	v_mov_b32_e32 v26, v32
	v_mov_b32_e32 v27, v32
	v_mov_b32_e32 v20, v32
	v_mov_b32_e32 v21, v32
	v_mov_b32_e32 v22, v32
	v_mov_b32_e32 v23, v32
	v_mov_b32_e32 v16, v32
	v_mov_b32_e32 v17, v32
	v_mov_b32_e32 v18, v32
	v_mov_b32_e32 v19, v32
	v_mov_b32_e32 v12, v32
	v_mov_b32_e32 v13, v32
	v_mov_b32_e32 v14, v32
	v_mov_b32_e32 v15, v32
	v_mov_b32_e32 v8, v32
	v_mov_b32_e32 v9, v32
	v_mov_b32_e32 v10, v32
	v_mov_b32_e32 v11, v32
	v_mov_b32_e32 v4, v32
	s_waitcnt lgkmcnt(0)
	v_mov_b32_e32 v5, v32
	v_mov_b32_e32 v6, v32
	v_mov_b32_e32 v7, v32
	v_mov_b32_e32 v0, v32
	v_mov_b32_e32 v1, v32
	v_mov_b32_e32 v2, v32
	v_mov_b32_e32 v3, v32
	s_branch .LBB0_188
	.p2align 6

; #define WAIT_V(n) asm volatile("s_waitcnt vmcnt(%0)" ::"n"(n) : "memory")
; template <class Epi>
; DEV void gemm_phase(const u16* __restrict__ A, int lda, const u16* __restrict__ Bt, int K, int nM, int nN, char* shm, const Epi& epi) {
;     ...
;   int t = blockIdx.x;
;   if (t >= nwg) return;
;   int brow, bcol;
;   tile_coords(t, nwg, nM, nN, brow, bcol);
;   const u16* Ab = A + (long)brow * lda;
;   const u16* Bb = Bt + (long)bcol * K;
;   int cur = 0;
;   __syncthreads();
;   GLDS_STAGE(0, Ab, Bb, 0); WAIT_V(0); __syncthreads();
;   for (;;) {
;     const int tn = t + gridDim.x;
;     const bool has_next = tn < nwg;
;     int nbrow = 0, nbcol = 0;
;     if (has_next) tile_coords(tn, nwg, nM, nN, nbrow, nbcol);
;     const u16* nAb = A + (long)nbrow * lda;
;     const u16* nBb = Bt + (long)nbcol * K;
;     f32x4 acc[8][4];
; #pragma unroll
;     for (int m = 0; m < 8; ++m)
; #pragma unroll
;       for (int n = 0; n < 4; ++n) acc[m][n] = f32x4{0.f, 0.f, 0.f, 0.f};
.LBB0_244:
	s_ashr_i32 s13, s12, 31
	s_mul_i32 s14, s72, 0x880
	s_lshl_b64 s[16:17], s[12:13], 10
	s_mul_hi_i32 s15, s72, 0x880
	s_add_u32 s28, s22, s14
	s_addc_u32 s29, s23, s15
	v_readlane_b32 s36, v247, 40
	v_readlane_b32 s37, v247, 41
	s_add_u32 s30, s36, s16
	s_addc_u32 s31, s37, s17
	s_add_u32 s24, s36, s24
	s_addc_u32 s25, s37, s25
	s_add_u32 s26, s22, s26
	v_mov_b32_e32 v32, 0
	s_addc_u32 s27, s23, s27
	v_lshl_add_u64 v[146:147], s[28:29], 0, v[128:129]
	v_lshl_add_u64 v[148:149], s[30:31], 0, v[130:131]
	v_lshl_add_u64 v[150:151], s[28:29], 0, v[132:133]
	v_lshl_add_u64 v[152:153], s[30:31], 0, v[134:135]
	v_lshl_add_u64 v[154:155], s[28:29], 0, v[136:137]
	v_lshl_add_u64 v[156:157], s[30:31], 0, v[138:139]
	v_lshl_add_u64 v[158:159], s[28:29], 0, v[140:141]
	v_lshl_add_u64 v[160:161], s[30:31], 0, v[142:143]
	s_mov_b32 s1, 0
	v_mov_b32_e32 v33, v32
	v_mov_b32_e32 v34, v32
	v_mov_b32_e32 v35, v32
	v_mov_b32_e32 v36, v32
	v_mov_b32_e32 v37, v32
	v_mov_b32_e32 v38, v32
	v_mov_b32_e32 v39, v32
	v_mov_b32_e32 v40, v32
	v_mov_b32_e32 v41, v32
	v_mov_b32_e32 v42, v32
	v_mov_b32_e32 v43, v32
	v_mov_b32_e32 v44, v32
	v_mov_b32_e32 v45, v32
	v_mov_b32_e32 v46, v32
	v_mov_b32_e32 v47, v32
	v_mov_b32_e32 v48, v32
	v_mov_b32_e32 v49, v32
	v_mov_b32_e32 v50, v32
	v_mov_b32_e32 v51, v32
	v_mov_b32_e32 v52, v32
	v_mov_b32_e32 v53, v32
	v_mov_b32_e32 v54, v32
	v_mov_b32_e32 v55, v32
	v_mov_b32_e32 v56, v32
	v_mov_b32_e32 v57, v32
	v_mov_b32_e32 v58, v32
	v_mov_b32_e32 v59, v32
	v_mov_b32_e32 v60, v32
	v_mov_b32_e32 v61, v32
	v_mov_b32_e32 v62, v32
	v_mov_b32_e32 v63, v32
	v_mov_b32_e32 v64, v32
	v_mov_b32_e32 v65, v32
	v_mov_b32_e32 v66, v32
	v_mov_b32_e32 v67, v32
	v_mov_b32_e32 v68, v32
	v_mov_b32_e32 v69, v32
	v_mov_b32_e32 v70, v32
	v_mov_b32_e32 v71, v32
	v_mov_b32_e32 v72, v32
	v_mov_b32_e32 v73, v32
	v_mov_b32_e32 v74, v32
	v_mov_b32_e32 v75, v32
	v_mov_b32_e32 v76, v32
	v_mov_b32_e32 v77, v32
	v_mov_b32_e32 v78, v32
	v_mov_b32_e32 v79, v32
	v_mov_b32_e32 v80, v32
	v_mov_b32_e32 v81, v32
	v_mov_b32_e32 v82, v32
	v_mov_b32_e32 v83, v32
	v_mov_b32_e32 v84, v32
	v_mov_b32_e32 v85, v32
	v_mov_b32_e32 v86, v32
	v_mov_b32_e32 v87, v32
	v_mov_b32_e32 v88, v32
	v_mov_b32_e32 v89, v32
	v_mov_b32_e32 v90, v32
	v_mov_b32_e32 v91, v32
	v_mov_b32_e32 v92, v32
	v_mov_b32_e32 v93, v32
	v_mov_b32_e32 v94, v32
	v_mov_b32_e32 v95, v32
	v_mov_b32_e32 v96, v32
	v_mov_b32_e32 v97, v32
	v_mov_b32_e32 v98, v32
	v_mov_b32_e32 v99, v32
	v_mov_b32_e32 v100, v32
	v_mov_b32_e32 v101, v32
	v_mov_b32_e32 v102, v32
	v_mov_b32_e32 v103, v32
	v_mov_b32_e32 v104, v32
	v_mov_b32_e32 v105, v32
	v_mov_b32_e32 v106, v32
	v_mov_b32_e32 v107, v32
	v_mov_b32_e32 v108, v32
	v_mov_b32_e32 v109, v32
	v_mov_b32_e32 v110, v32
	v_mov_b32_e32 v111, v32
	v_mov_b32_e32 v112, v32
	v_mov_b32_e32 v113, v32
	v_mov_b32_e32 v114, v32
	v_mov_b32_e32 v115, v32
	v_mov_b32_e32 v116, v32
	v_mov_b32_e32 v117, v32
	v_mov_b32_e32 v118, v32
	v_mov_b32_e32 v119, v32
	v_mov_b32_e32 v120, v32
	v_mov_b32_e32 v121, v32
	v_mov_b32_e32 v122, v32
	v_mov_b32_e32 v123, v32
	v_mov_b32_e32 v124, v32
	v_mov_b32_e32 v125, v32
	v_mov_b32_e32 v126, v32
	v_mov_b32_e32 v127, v32
	v_mov_b32_e32 v28, v32
	v_mov_b32_e32 v29, v32
	v_mov_b32_e32 v30, v32
	v_mov_b32_e32 v31, v32
	v_mov_b32_e32 v24, v32
	v_mov_b32_e32 v25, v32
	v_mov_b32_e32 v26, v32
	v_mov_b32_e32 v27, v32
	v_mov_b32_e32 v20, v32
	v_mov_b32_e32 v21, v32
	v_mov_b32_e32 v22, v32
	v_mov_b32_e32 v23, v32
	v_mov_b32_e32 v16, v32
	v_mov_b32_e32 v17, v32
	v_mov_b32_e32 v18, v32
	v_mov_b32_e32 v19, v32
	v_mov_b32_e32 v12, v32
	v_mov_b32_e32 v13, v32
	v_mov_b32_e32 v14, v32
	v_mov_b32_e32 v15, v32
	v_mov_b32_e32 v8, v32
	v_mov_b32_e32 v9, v32
	v_mov_b32_e32 v10, v32
	v_mov_b32_e32 v11, v32
	v_mov_b32_e32 v4, v32
	v_mov_b32_e32 v5, v32
	v_mov_b32_e32 v6, v32
	v_mov_b32_e32 v7, v32
	v_mov_b32_e32 v0, v32
	v_mov_b32_e32 v1, v32
	v_mov_b32_e32 v2, v32
	v_mov_b32_e32 v3, v32
	s_branch .LBB0_246
	.p2align 6

; #define WAIT_V(n) asm volatile("s_waitcnt vmcnt(%0)" ::"n"(n) : "memory")
; template <class Epi>
; DEV void gemm_phase(const u16* __restrict__ A, int lda, const u16* __restrict__ Bt, int K, int nM, int nN, char* shm, const Epi& epi) {
;     ...
;   int t = blockIdx.x;
;   if (t >= nwg) return;
;   int brow, bcol;
;   tile_coords(t, nwg, nM, nN, brow, bcol);
;   const u16* Ab = A + (long)brow * lda;
;   const u16* Bb = Bt + (long)bcol * K;
;   int cur = 0;
;   __syncthreads();
;   GLDS_STAGE(0, Ab, Bb, 0); WAIT_V(0); __syncthreads();
;   for (;;) {
;     const int tn = t + gridDim.x;
;     const bool has_next = tn < nwg;
;     int nbrow = 0, nbcol = 0;
;     if (has_next) tile_coords(tn, nwg, nM, nN, nbrow, nbcol);
;     const u16* nAb = A + (long)nbrow * lda;
;     const u16* nBb = Bt + (long)nbcol * K;
;     f32x4 acc[8][4];
; #pragma unroll
;     for (int m = 0; m < 8; ++m)
; #pragma unroll
;       for (int n = 0; n < 4; ++n) acc[m][n] = f32x4{0.f, 0.f, 0.f, 0.f};
.LBB0_275:
	s_ashr_i32 s7, s6, 31
	s_mul_i32 s8, s62, 0x880
	s_lshl_b64 s[10:11], s[6:7], 10
	s_mul_hi_i32 s9, s62, 0x880
	s_add_u32 s26, s30, s8
	s_addc_u32 s27, s31, s9
	v_readlane_b32 s36, v247, 38
	v_readlane_b32 s37, v247, 39
	s_add_u32 s28, s36, s10
	s_addc_u32 s29, s37, s11
	s_add_u32 s16, s36, s16
	s_addc_u32 s17, s37, s17
	s_add_u32 s18, s30, s18
	v_mov_b32_e32 v32, 0
	s_addc_u32 s19, s31, s19
	v_lshl_add_u64 v[146:147], s[26:27], 0, v[128:129]
	v_lshl_add_u64 v[148:149], s[28:29], 0, v[130:131]
	v_lshl_add_u64 v[150:151], s[26:27], 0, v[132:133]
	v_lshl_add_u64 v[152:153], s[28:29], 0, v[134:135]
	v_lshl_add_u64 v[154:155], s[26:27], 0, v[136:137]
	v_lshl_add_u64 v[156:157], s[28:29], 0, v[138:139]
	v_lshl_add_u64 v[158:159], s[26:27], 0, v[140:141]
	v_lshl_add_u64 v[160:161], s[28:29], 0, v[142:143]
	s_mov_b32 s1, 0
	v_mov_b32_e32 v33, v32
	v_mov_b32_e32 v34, v32
	v_mov_b32_e32 v35, v32
	v_mov_b32_e32 v36, v32
	v_mov_b32_e32 v37, v32
	v_mov_b32_e32 v38, v32
	v_mov_b32_e32 v39, v32
	v_mov_b32_e32 v40, v32
	v_mov_b32_e32 v41, v32
	v_mov_b32_e32 v42, v32
	v_mov_b32_e32 v43, v32
	v_mov_b32_e32 v44, v32
	v_mov_b32_e32 v45, v32
	v_mov_b32_e32 v46, v32
	v_mov_b32_e32 v47, v32
	v_mov_b32_e32 v48, v32
	v_mov_b32_e32 v49, v32
	v_mov_b32_e32 v50, v32
	v_mov_b32_e32 v51, v32
	v_mov_b32_e32 v52, v32
	v_mov_b32_e32 v53, v32
	v_mov_b32_e32 v54, v32
	v_mov_b32_e32 v55, v32
	v_mov_b32_e32 v56, v32
	v_mov_b32_e32 v57, v32
	v_mov_b32_e32 v58, v32
	v_mov_b32_e32 v59, v32
	v_mov_b32_e32 v60, v32
	v_mov_b32_e32 v61, v32
	v_mov_b32_e32 v62, v32
	v_mov_b32_e32 v63, v32
	v_mov_b32_e32 v64, v32
	v_mov_b32_e32 v65, v32
	v_mov_b32_e32 v66, v32
	v_mov_b32_e32 v67, v32
	v_mov_b32_e32 v68, v32
	v_mov_b32_e32 v69, v32
	v_mov_b32_e32 v70, v32
	v_mov_b32_e32 v71, v32
	v_mov_b32_e32 v72, v32
	v_mov_b32_e32 v73, v32
	v_mov_b32_e32 v74, v32
	v_mov_b32_e32 v75, v32
	v_mov_b32_e32 v76, v32
	v_mov_b32_e32 v77, v32
	v_mov_b32_e32 v78, v32
	v_mov_b32_e32 v79, v32
	v_mov_b32_e32 v80, v32
	v_mov_b32_e32 v81, v32
	v_mov_b32_e32 v82, v32
	v_mov_b32_e32 v83, v32
	v_mov_b32_e32 v84, v32
	v_mov_b32_e32 v85, v32
	v_mov_b32_e32 v86, v32
	v_mov_b32_e32 v87, v32
	v_mov_b32_e32 v88, v32
	v_mov_b32_e32 v89, v32
	v_mov_b32_e32 v90, v32
	v_mov_b32_e32 v91, v32
	v_mov_b32_e32 v92, v32
	v_mov_b32_e32 v93, v32
	v_mov_b32_e32 v94, v32
	v_mov_b32_e32 v95, v32
	v_mov_b32_e32 v96, v32
	v_mov_b32_e32 v97, v32
	v_mov_b32_e32 v98, v32
	v_mov_b32_e32 v99, v32
	v_mov_b32_e32 v100, v32
	v_mov_b32_e32 v101, v32
	v_mov_b32_e32 v102, v32
	v_mov_b32_e32 v103, v32
	v_mov_b32_e32 v104, v32
	v_mov_b32_e32 v105, v32
	v_mov_b32_e32 v106, v32
	v_mov_b32_e32 v107, v32
	v_mov_b32_e32 v108, v32
	v_mov_b32_e32 v109, v32
	v_mov_b32_e32 v110, v32
	v_mov_b32_e32 v111, v32
	v_mov_b32_e32 v112, v32
	v_mov_b32_e32 v113, v32
	v_mov_b32_e32 v114, v32
	v_mov_b32_e32 v115, v32
	v_mov_b32_e32 v116, v32
	v_mov_b32_e32 v117, v32
	v_mov_b32_e32 v118, v32
	v_mov_b32_e32 v119, v32
	v_mov_b32_e32 v120, v32
	v_mov_b32_e32 v121, v32
	v_mov_b32_e32 v122, v32
	v_mov_b32_e32 v123, v32
	v_mov_b32_e32 v124, v32
	v_mov_b32_e32 v125, v32
	v_mov_b32_e32 v126, v32
	v_mov_b32_e32 v127, v32
	v_mov_b32_e32 v16, v32
	v_mov_b32_e32 v17, v32
	v_mov_b32_e32 v18, v32
	v_mov_b32_e32 v19, v32
	v_mov_b32_e32 v20, v32
	v_mov_b32_e32 v21, v32
	v_mov_b32_e32 v22, v32
	v_mov_b32_e32 v23, v32
	v_mov_b32_e32 v24, v32
	v_mov_b32_e32 v25, v32
	v_mov_b32_e32 v26, v32
	v_mov_b32_e32 v27, v32
	v_mov_b32_e32 v28, v32
	v_mov_b32_e32 v29, v32
	v_mov_b32_e32 v30, v32
	v_mov_b32_e32 v31, v32
	v_mov_b32_e32 v0, v32
	v_mov_b32_e32 v1, v32
	v_mov_b32_e32 v2, v32
	v_mov_b32_e32 v3, v32
	v_mov_b32_e32 v4, v32
	v_mov_b32_e32 v5, v32
	v_mov_b32_e32 v6, v32
	v_mov_b32_e32 v7, v32
	v_mov_b32_e32 v8, v32
	v_mov_b32_e32 v9, v32
	v_mov_b32_e32 v10, v32
	v_mov_b32_e32 v11, v32
	v_mov_b32_e32 v12, v32
	v_mov_b32_e32 v13, v32
	v_mov_b32_e32 v14, v32
	v_mov_b32_e32 v15, v32
	s_branch .LBB0_277
	.p2align 6

; DEV void scan_job(const P& p, int job, char* shm) {
;     ...
;     if (is_scan) {
;       const float* base = lbase + (c & 1) * (6 * ASZ) + np * 8;
;       const float* vbase = lbase + (c & 1) * (6 * ASZ) + 5 * ASZ + 2 * rp;
;       const int tstep = d ? -SLD : SLD;
;       int toff = d ? (TC - 1) * SLD : 0;
;     ...
;       f32x4 Aw0, Aw1, Aq0, Aq1, Ab0, Ab1, Ad0, Ad1, Ar0, Ar1; f32x2 Avv;
;       f32x4 Bw0, Bw1, Bq0, Bq1, Bb0, Bb1, Bd0, Bd1, Br0, Br1; f32x2 Bvv;
;       float yk0 = 0.f, yk1 = 0.f;
;       LOADOPS(A, toff);
.LBB0_1504:
	s_or_saveexec_b64 s[28:29], s[44:45]
	s_and_b32 s44, s35, 1
	s_xor_b64 exec, exec, s[28:29]
	s_cbranch_execz .LBB0_1509
	s_mul_i32 s40, s44, 0xcc00
	v_cndmask_b32_e64 v0, 0, 1, s[42:43]
	s_add_i32 s40, s1, s40
	v_mul_lo_u32 v1, v0, s0
	v_add_u32_e32 v4, s40, v140
	v_add_u32_e32 v156, v145, v1
	v_mul_lo_u32 v44, v0, s51
	ds_read_b128 v[28:31], v4
	ds_read_b128 v[0:3], v4 offset:16
	ds_read_b128 v[36:39], v4 offset:8704
	ds_read_b128 v[32:35], v4 offset:8720
	ds_read_b128 v[24:27], v4 offset:17408
	ds_read_b128 v[8:11], v4 offset:17424
	ds_read_b128 v[20:23], v4 offset:26112
	ds_read_b128 v[12:15], v4 offset:26128
	ds_read_b128 v[16:19], v4 offset:34816
	ds_read_b128 v[4:7], v4 offset:34832
	v_lshl_add_u32 v45, v141, 2, s40
	ds_read_b64 v[98:99], v45 offset:43520
	v_mov_b32_e32 v90, 0
	v_add_u32_e32 v157, v146, v44
	v_add_u32_e32 v158, v147, v44
	v_add_u32_e32 v159, v148, v44
	v_add_u32_e32 v160, v149, v44
	s_mov_b32 s45, -8
	v_mov_b32_e32 v91, v90
	s_branch .LBB0_1507
	.p2align 6

; #define WAIT_V(n) asm volatile("s_waitcnt vmcnt(%0)" ::"n"(n) : "memory")
; template <class Epi>
; DEV void gemm_phase(const u16* __restrict__ A, int lda, const u16* __restrict__ Bt, int K, int nM, int nN, char* shm, const Epi& epi) {
;     ...
;   int t = blockIdx.x;
;   if (t >= nwg) return;
;   int brow, bcol;
;   tile_coords(t, nwg, nM, nN, brow, bcol);
;   const u16* Ab = A + (long)brow * lda;
;   const u16* Bb = Bt + (long)bcol * K;
;   int cur = 0;
;   __syncthreads();
;   GLDS_STAGE(0, Ab, Bb, 0); WAIT_V(0); __syncthreads();
;   for (;;) {
;     const int tn = t + gridDim.x;
;     const bool has_next = tn < nwg;
;     int nbrow = 0, nbcol = 0;
;     if (has_next) tile_coords(tn, nwg, nM, nN, nbrow, nbcol);
;     const u16* nAb = A + (long)nbrow * lda;
;     const u16* nBb = Bt + (long)nbcol * K;
;     f32x4 acc[8][4];
; #pragma unroll
;     for (int m = 0; m < 8; ++m)
; #pragma unroll
;       for (int n = 0; n < 4; ++n) acc[m][n] = f32x4{0.f, 0.f, 0.f, 0.f};
.LBB0_1527:
	s_ashr_i32 s11, s10, 31
	s_mul_i32 s12, s42, 0x600
	s_lshl_b64 s[14:15], s[10:11], 9
	s_mul_hi_i32 s13, s42, 0x600
	s_add_u32 s24, s3, s12
	s_addc_u32 s25, s28, s13
	s_add_u32 s26, s64, s14
	s_addc_u32 s27, s65, s15
	s_add_u32 s20, s64, s20
	s_addc_u32 s21, s65, s21
	s_add_u32 s22, s3, s22
	v_mov_b32_e32 v32, 0
	s_addc_u32 s23, s28, s23
	v_lshl_add_u64 v[146:147], s[24:25], 0, v[128:129]
	v_lshl_add_u64 v[148:149], s[26:27], 0, v[130:131]
	v_lshl_add_u64 v[150:151], s[24:25], 0, v[132:133]
	v_lshl_add_u64 v[152:153], s[26:27], 0, v[134:135]
	v_lshl_add_u64 v[154:155], s[24:25], 0, v[136:137]
	v_lshl_add_u64 v[156:157], s[26:27], 0, v[138:139]
	v_lshl_add_u64 v[158:159], s[24:25], 0, v[140:141]
	v_lshl_add_u64 v[160:161], s[26:27], 0, v[142:143]
	s_mov_b32 s1, 0
	v_mov_b32_e32 v33, v32
	v_mov_b32_e32 v34, v32
	v_mov_b32_e32 v35, v32
	v_mov_b32_e32 v36, v32
	v_mov_b32_e32 v37, v32
	v_mov_b32_e32 v38, v32
	v_mov_b32_e32 v39, v32
	v_mov_b32_e32 v40, v32
	v_mov_b32_e32 v41, v32
	v_mov_b32_e32 v42, v32
	v_mov_b32_e32 v43, v32
	v_mov_b32_e32 v44, v32
	v_mov_b32_e32 v45, v32
	v_mov_b32_e32 v46, v32
	v_mov_b32_e32 v47, v32
	v_mov_b32_e32 v48, v32
	v_mov_b32_e32 v49, v32
	v_mov_b32_e32 v50, v32
	v_mov_b32_e32 v51, v32
	v_mov_b32_e32 v52, v32
	v_mov_b32_e32 v53, v32
	v_mov_b32_e32 v54, v32
	v_mov_b32_e32 v55, v32
	v_mov_b32_e32 v56, v32
	v_mov_b32_e32 v57, v32
	v_mov_b32_e32 v58, v32
	v_mov_b32_e32 v59, v32
	v_mov_b32_e32 v60, v32
	v_mov_b32_e32 v61, v32
	v_mov_b32_e32 v62, v32
	v_mov_b32_e32 v63, v32
	v_mov_b32_e32 v64, v32
	v_mov_b32_e32 v65, v32
	v_mov_b32_e32 v66, v32
	v_mov_b32_e32 v67, v32
	v_mov_b32_e32 v68, v32
	v_mov_b32_e32 v69, v32
	v_mov_b32_e32 v70, v32
	v_mov_b32_e32 v71, v32
	v_mov_b32_e32 v72, v32
	v_mov_b32_e32 v73, v32
	v_mov_b32_e32 v74, v32
	v_mov_b32_e32 v75, v32
	v_mov_b32_e32 v76, v32
	v_mov_b32_e32 v77, v32
	v_mov_b32_e32 v78, v32
	v_mov_b32_e32 v79, v32
	v_mov_b32_e32 v80, v32
	v_mov_b32_e32 v81, v32
	v_mov_b32_e32 v82, v32
	v_mov_b32_e32 v83, v32
	v_mov_b32_e32 v84, v32
	v_mov_b32_e32 v85, v32
	v_mov_b32_e32 v86, v32
	v_mov_b32_e32 v87, v32
	v_mov_b32_e32 v88, v32
	v_mov_b32_e32 v89, v32
	v_mov_b32_e32 v90, v32
	v_mov_b32_e32 v91, v32
	v_mov_b32_e32 v92, v32
	v_mov_b32_e32 v93, v32
	v_mov_b32_e32 v94, v32
	v_mov_b32_e32 v95, v32
	v_mov_b32_e32 v96, v32
	v_mov_b32_e32 v97, v32
	v_mov_b32_e32 v98, v32
	v_mov_b32_e32 v99, v32
	v_mov_b32_e32 v100, v32
	v_mov_b32_e32 v101, v32
	v_mov_b32_e32 v102, v32
	v_mov_b32_e32 v103, v32
	v_mov_b32_e32 v104, v32
	v_mov_b32_e32 v105, v32
	v_mov_b32_e32 v106, v32
	v_mov_b32_e32 v107, v32
	v_mov_b32_e32 v108, v32
	v_mov_b32_e32 v109, v32
	v_mov_b32_e32 v110, v32
	v_mov_b32_e32 v111, v32
	v_mov_b32_e32 v112, v32
	v_mov_b32_e32 v113, v32
	v_mov_b32_e32 v114, v32
	v_mov_b32_e32 v115, v32
	v_mov_b32_e32 v116, v32
	v_mov_b32_e32 v117, v32
	v_mov_b32_e32 v118, v32
	v_mov_b32_e32 v119, v32
	v_mov_b32_e32 v120, v32
	v_mov_b32_e32 v121, v32
	v_mov_b32_e32 v122, v32
	v_mov_b32_e32 v123, v32
	v_mov_b32_e32 v124, v32
	v_mov_b32_e32 v125, v32
	v_mov_b32_e32 v126, v32
	v_mov_b32_e32 v127, v32
	v_mov_b32_e32 v28, v32
	v_mov_b32_e32 v29, v32
	v_mov_b32_e32 v30, v32
	v_mov_b32_e32 v31, v32
	v_mov_b32_e32 v24, v32
	v_mov_b32_e32 v25, v32
	v_mov_b32_e32 v26, v32
	v_mov_b32_e32 v27, v32
	v_mov_b32_e32 v20, v32
	v_mov_b32_e32 v21, v32
	v_mov_b32_e32 v22, v32
	v_mov_b32_e32 v23, v32
	v_mov_b32_e32 v16, v32
	v_mov_b32_e32 v17, v32
	v_mov_b32_e32 v18, v32
	v_mov_b32_e32 v19, v32
	v_mov_b32_e32 v12, v32
	v_mov_b32_e32 v13, v32
	v_mov_b32_e32 v14, v32
	v_mov_b32_e32 v15, v32
	v_mov_b32_e32 v8, v32
	v_mov_b32_e32 v9, v32
	v_mov_b32_e32 v10, v32
	v_mov_b32_e32 v11, v32
	v_mov_b32_e32 v4, v32
	v_mov_b32_e32 v5, v32
	v_mov_b32_e32 v6, v32
	v_mov_b32_e32 v7, v32
	v_mov_b32_e32 v0, v32
	v_mov_b32_e32 v1, v32
	v_mov_b32_e32 v2, v32
	v_mov_b32_e32 v3, v32
	s_branch .LBB0_1529
	.p2align 6
